# sb_phase: gate loads issued up front with counted waits, Q loads hoisted so next-unit K/V prefetch overlaps compute; select: one multi-lane atomic per step
# speedup vs baseline: 1.0128x; 1.0128x over previous
.LBB0_177:
	s_or_b64 exec, exec, s[0:1]
	s_and_b32 s0, s20, 3
	s_or_b32 s0, s0, s34
	s_lshl_b32 s0, s0, 5
	v_lshlrev_b32_e32 v32, 8, v75
	v_or3_b32 v32, s0, v32, v198
	s_mov_b64 s[18:19], 0
	s_mov_b64 s[20:21], s[14:15]
	s_mov_b64 s[22:23], s[12:13]
	v_mov_b32_e32 v140, v114
	v_mov_b32_e32 v141, v34
	v_mov_b32_e32 v142, v35
	v_mov_b32_e32 v143, 0
	v_lshlrev_b32_e32 v147, 2, v189
	v_readfirstlane_b32 s73, v75
	s_mov_b32 s72, 0
.Lsel_cnt_loop:
	v_subrev_co_u32_e64 v140, s[0:1], 1, v140
	v_subrev_co_u32_e64 v141, s[6:7], 1, v141
	s_or_b64 s[8:9], s[0:1], s[6:7]
	v_subrev_co_u32_e32 v142, vcc, 1, v142
	s_or_b64 s[8:9], s[8:9], vcc
	s_and_b64 s[24:25], s[4:5], s[8:9]
	s_nop 0
	v_cndmask_b32_e64 v148, 0, 1, s[24:25]
	v_cmp_ne_u32_e32 vcc, 0, v148
	s_mov_b32 m0, s72
	s_bcnt1_i32_b64 s74, vcc
	s_add_i32 s72, s72, 1
	v_writelane_b32 v143, s74, m0
	s_cmp_lt_u32 s72, s73
	s_cbranch_scc1 .Lsel_cnt_loop
	v_cmp_ne_u32_e32 vcc, 0, v143
	s_and_saveexec_b64 s[26:27], vcc
	s_cbranch_execz .Lsel_cnt_done
	global_atomic_add v146, v147, v143, s[12:13] sc0
.Lsel_cnt_done:
	s_or_b64 exec, exec, s[26:27]
	s_mov_b32 s72, 0
	s_waitcnt vmcnt(0)
	s_branch .LBB0_180

.LBB0_179:
	s_add_i32 s72, s72, 1
	s_add_u32 s22, s22, 4
	s_addc_u32 s23, s23, 0
	s_add_u32 s20, s20, 0x2000
	v_add_u32_e32 v75, -1, v75
	s_addc_u32 s21, s21, 0
	v_cmp_eq_u32_e32 vcc, 0, v75
	s_or_b64 s[18:19], vcc, s[18:19]
	s_andn2_b64 exec, exec, s[18:19]
	s_cbranch_execz .LBB0_167
.LBB0_180:
	v_subrev_co_u32_e64 v114, s[0:1], 1, v114
	v_subrev_co_u32_e64 v34, s[6:7], 1, v34
	s_or_b64 s[8:9], s[0:1], s[6:7]
	v_subrev_co_u32_e32 v35, vcc, 1, v35
	s_or_b64 s[8:9], s[8:9], vcc
	s_and_b64 s[24:25], s[4:5], s[8:9]
	s_waitcnt lgkmcnt(0)
	v_cndmask_b32_e64 v33, 0, 1, s[24:25]
	v_cmp_ne_u32_e32 vcc, 0, v33
	s_cbranch_vccz .LBB0_179
	v_readlane_b32 s36, v146, s72
	s_and_saveexec_b64 s[8:9], s[24:25]
	s_cbranch_execz .LBB0_178
	v_and_b32_e32 v37, vcc_lo, v64
	v_and_b32_e32 v36, vcc_hi, v65
	v_bcnt_u32_b32 v37, v37, 0
	v_bcnt_u32_b32 v36, v36, v37
	v_add_u32_e32 v36, s36, v36
	v_cndmask_b32_e64 v33, v73, v74, s[6:7]
	v_cndmask_b32_e64 v33, v33, 0, s[0:1]
	v_ashrrev_i32_e32 v37, 31, v36
	v_lshl_add_u64 v[36:37], v[36:37], 1, s[20:21]
	v_or_b32_e32 v33, v32, v33
	global_store_short v[36:37], v33, off sc1
	s_branch .LBB0_178

.LBB0_208:
	s_or_b64 exec, exec, s[12:13]
	s_ashr_i32 s0, s5, 7
	s_ashr_i32 s1, s0, 31
	s_lshl_b64 s[0:1], s[0:1], 12
	v_mov_b32_e32 v169, v133
	v_lshl_add_u64 v[48:49], s[0:1], 0, v[168:169]
	v_or_b32_e32 v48, v48, v146
	v_readlane_b32 s16, v255, 12
	v_lshlrev_b64 v[48:49], 11, v[48:49]
	v_readlane_b32 s30, v255, 26
	v_readlane_b32 s31, v255, 27
	s_lshl_b32 s0, s98, 7
	s_and_b32 s54, s0, 0x380
	v_lshl_add_u64 v[50:51], s[30:31], 0, v[48:49]
	v_lshl_add_u64 v[50:51], v[50:51], 0, s[54:55]
	v_lshlrev_b32_e32 v132, 1, v122
	v_lshl_add_u64 v[50:51], v[50:51], 0, v[132:133]
	global_load_dwordx2 v[96:97], v[50:51], off
	global_load_dwordx2 v[98:99], v[50:51], off offset:32
	global_load_dwordx2 v[100:101], v[50:51], off offset:64
	global_load_dwordx2 v[102:103], v[50:51], off offset:96
	v_readlane_b32 s12, v254, 2
	v_readlane_b32 s13, v254, 3
	v_readlane_b32 s17, v255, 13
	v_readlane_b32 s20, v255, 16
	v_lshl_add_u64 v[54:55], s[12:13], 0, v[48:49]
	v_lshl_add_u64 v[54:55], v[54:55], 0, s[54:55]
	v_lshl_add_u64 v[54:55], v[54:55], 0, v[132:133]
	v_or_b32_e32 v48, 0x8000, v48
	v_lshl_add_u64 v[52:53], s[30:31], 0, v[48:49]
	v_lshl_add_u64 v[52:53], v[52:53], 0, s[54:55]
	v_lshl_add_u64 v[52:53], v[52:53], 0, v[132:133]
	v_lshl_add_u64 v[48:49], s[12:13], 0, v[48:49]
	v_lshl_add_u64 v[48:49], v[48:49], 0, s[54:55]
	v_lshl_add_u64 v[48:49], v[48:49], 0, v[132:133]
	global_load_dwordx2 v[104:105], v[52:53], off
	global_load_dwordx2 v[106:107], v[52:53], off offset:32
	global_load_dwordx2 v[108:109], v[52:53], off offset:64
	global_load_dwordx2 v[110:111], v[52:53], off offset:96
	v_readlane_b32 s21, v255, 17
	v_readlane_b32 s24, v255, 20
	v_readlane_b32 s25, v255, 21
	v_readlane_b32 s26, v255, 22
	v_readlane_b32 s27, v255, 23
	v_readlane_b32 s28, v255, 24
	v_readlane_b32 s29, v255, 25
	s_add_i32 s33, s33, s43
	s_andn2_b64 vcc, exec, s[80:81]
	s_mov_b32 s5, s4
	v_readlane_b32 s18, v255, 14
	v_readlane_b32 s19, v255, 15
	v_readlane_b32 s22, v255, 18
	v_readlane_b32 s23, v255, 19
	v_readlane_b32 s14, v254, 4
	v_readlane_b32 s15, v254, 5
	s_waitcnt vmcnt(7)
	v_lshlrev_b32_e32 v56, 16, v96
	v_and_b32_e32 v57, 0xffff0000, v96
	v_lshlrev_b32_e32 v112, 16, v97
	v_and_b32_e32 v113, 0xffff0000, v97
	v_mul_f32_e32 v58, 0xbfb8aa3b, v56
	v_mul_f32_e32 v59, 0xbfb8aa3b, v57
	v_mul_f32_e32 v60, 0xbfb8aa3b, v112
	v_mul_f32_e32 v61, 0xbfb8aa3b, v113
	v_exp_f32_e32 v58, v58
	v_exp_f32_e32 v59, v59
	v_exp_f32_e32 v60, v60
	v_exp_f32_e32 v61, v61
	v_add_f32_e32 v58, 1.0, v58
	v_add_f32_e32 v59, 1.0, v59
	v_add_f32_e32 v60, 1.0, v60
	v_add_f32_e32 v61, 1.0, v61
	v_rcp_f32_e32 v58, v58
	v_rcp_f32_e32 v59, v59
	v_rcp_f32_e32 v60, v60
	v_rcp_f32_e32 v61, v61
	v_pk_mul_f32 v[56:57], v[92:93], v[56:57]
	v_pk_mul_f32 v[112:113], v[94:95], v[112:113]
	v_pk_mul_f32 v[56:57], v[56:57], v[58:59]
	v_pk_mul_f32 v[112:113], v[112:113], v[60:61]
	v_cvt_pk_bf16_f32 v56, v56, v57
	v_cvt_pk_bf16_f32 v57, v112, v113
	global_store_dwordx2 v[54:55], v[56:57], off
	s_waitcnt vmcnt(7)
	v_lshlrev_b32_e32 v56, 16, v98
	v_and_b32_e32 v57, 0xffff0000, v98
	v_lshlrev_b32_e32 v112, 16, v99
	v_and_b32_e32 v113, 0xffff0000, v99
	v_mul_f32_e32 v58, 0xbfb8aa3b, v56
	v_mul_f32_e32 v59, 0xbfb8aa3b, v57
	v_mul_f32_e32 v60, 0xbfb8aa3b, v112
	v_mul_f32_e32 v61, 0xbfb8aa3b, v113
	v_exp_f32_e32 v58, v58
	v_exp_f32_e32 v59, v59
	v_exp_f32_e32 v60, v60
	v_exp_f32_e32 v61, v61
	v_add_f32_e32 v58, 1.0, v58
	v_add_f32_e32 v59, 1.0, v59
	v_add_f32_e32 v60, 1.0, v60
	v_add_f32_e32 v61, 1.0, v61
	v_rcp_f32_e32 v58, v58
	v_rcp_f32_e32 v59, v59
	v_rcp_f32_e32 v60, v60
	v_rcp_f32_e32 v61, v61
	v_pk_mul_f32 v[56:57], v[88:89], v[56:57]
	v_pk_mul_f32 v[112:113], v[90:91], v[112:113]
	v_pk_mul_f32 v[56:57], v[56:57], v[58:59]
	v_pk_mul_f32 v[112:113], v[112:113], v[60:61]
	v_cvt_pk_bf16_f32 v56, v56, v57
	v_cvt_pk_bf16_f32 v57, v112, v113
	global_store_dwordx2 v[54:55], v[56:57], off offset:32
	s_waitcnt vmcnt(7)
	v_lshlrev_b32_e32 v56, 16, v100
	v_and_b32_e32 v57, 0xffff0000, v100
	v_lshlrev_b32_e32 v112, 16, v101
	v_and_b32_e32 v113, 0xffff0000, v101
	v_mul_f32_e32 v58, 0xbfb8aa3b, v56
	v_mul_f32_e32 v59, 0xbfb8aa3b, v57
	v_mul_f32_e32 v60, 0xbfb8aa3b, v112
	v_mul_f32_e32 v61, 0xbfb8aa3b, v113
	v_exp_f32_e32 v58, v58
	v_exp_f32_e32 v59, v59
	v_exp_f32_e32 v60, v60
	v_exp_f32_e32 v61, v61
	v_add_f32_e32 v58, 1.0, v58
	v_add_f32_e32 v59, 1.0, v59
	v_add_f32_e32 v60, 1.0, v60
	v_add_f32_e32 v61, 1.0, v61
	v_rcp_f32_e32 v58, v58
	v_rcp_f32_e32 v59, v59
	v_rcp_f32_e32 v60, v60
	v_rcp_f32_e32 v61, v61
	v_pk_mul_f32 v[56:57], v[84:85], v[56:57]
	v_pk_mul_f32 v[112:113], v[86:87], v[112:113]
	v_pk_mul_f32 v[56:57], v[56:57], v[58:59]
	v_pk_mul_f32 v[112:113], v[112:113], v[60:61]
	v_cvt_pk_bf16_f32 v56, v56, v57
	v_cvt_pk_bf16_f32 v57, v112, v113
	global_store_dwordx2 v[54:55], v[56:57], off offset:64
	s_waitcnt vmcnt(7)
	v_lshlrev_b32_e32 v56, 16, v102
	v_and_b32_e32 v57, 0xffff0000, v102
	v_lshlrev_b32_e32 v112, 16, v103
	v_and_b32_e32 v113, 0xffff0000, v103
	v_mul_f32_e32 v58, 0xbfb8aa3b, v56
	v_mul_f32_e32 v59, 0xbfb8aa3b, v57
	v_mul_f32_e32 v60, 0xbfb8aa3b, v112
	v_mul_f32_e32 v61, 0xbfb8aa3b, v113
	v_exp_f32_e32 v58, v58
	v_exp_f32_e32 v59, v59
	v_exp_f32_e32 v60, v60
	v_exp_f32_e32 v61, v61
	v_add_f32_e32 v58, 1.0, v58
	v_add_f32_e32 v59, 1.0, v59
	v_add_f32_e32 v60, 1.0, v60
	v_add_f32_e32 v61, 1.0, v61
	v_rcp_f32_e32 v58, v58
	v_rcp_f32_e32 v59, v59
	v_rcp_f32_e32 v60, v60
	v_rcp_f32_e32 v61, v61
	v_pk_mul_f32 v[56:57], v[80:81], v[56:57]
	v_pk_mul_f32 v[112:113], v[82:83], v[112:113]
	v_pk_mul_f32 v[56:57], v[56:57], v[58:59]
	v_pk_mul_f32 v[112:113], v[112:113], v[60:61]
	v_cvt_pk_bf16_f32 v56, v56, v57
	v_cvt_pk_bf16_f32 v57, v112, v113
	global_store_dwordx2 v[54:55], v[56:57], off offset:96
	s_waitcnt vmcnt(7)
	v_lshlrev_b32_e32 v56, 16, v104
	v_and_b32_e32 v57, 0xffff0000, v104
	v_lshlrev_b32_e32 v112, 16, v105
	v_and_b32_e32 v113, 0xffff0000, v105
	v_mul_f32_e32 v58, 0xbfb8aa3b, v56
	v_mul_f32_e32 v59, 0xbfb8aa3b, v57
	v_mul_f32_e32 v60, 0xbfb8aa3b, v112
	v_mul_f32_e32 v61, 0xbfb8aa3b, v113
	v_exp_f32_e32 v58, v58
	v_exp_f32_e32 v59, v59
	v_exp_f32_e32 v60, v60
	v_exp_f32_e32 v61, v61
	v_add_f32_e32 v58, 1.0, v58
	v_add_f32_e32 v59, 1.0, v59
	v_add_f32_e32 v60, 1.0, v60
	v_add_f32_e32 v61, 1.0, v61
	v_rcp_f32_e32 v58, v58
	v_rcp_f32_e32 v59, v59
	v_rcp_f32_e32 v60, v60
	v_rcp_f32_e32 v61, v61
	v_pk_mul_f32 v[56:57], v[76:77], v[56:57]
	v_pk_mul_f32 v[112:113], v[78:79], v[112:113]
	v_pk_mul_f32 v[56:57], v[56:57], v[58:59]
	v_pk_mul_f32 v[112:113], v[112:113], v[60:61]
	v_cvt_pk_bf16_f32 v56, v56, v57
	v_cvt_pk_bf16_f32 v57, v112, v113
	global_store_dwordx2 v[48:49], v[56:57], off
	s_waitcnt vmcnt(7)
	v_lshlrev_b32_e32 v56, 16, v106
	v_and_b32_e32 v57, 0xffff0000, v106
	v_lshlrev_b32_e32 v112, 16, v107
	v_and_b32_e32 v113, 0xffff0000, v107
	v_mul_f32_e32 v58, 0xbfb8aa3b, v56
	v_mul_f32_e32 v59, 0xbfb8aa3b, v57
	v_mul_f32_e32 v60, 0xbfb8aa3b, v112
	v_mul_f32_e32 v61, 0xbfb8aa3b, v113
	v_exp_f32_e32 v58, v58
	v_exp_f32_e32 v59, v59
	v_exp_f32_e32 v60, v60
	v_exp_f32_e32 v61, v61
	v_add_f32_e32 v58, 1.0, v58
	v_add_f32_e32 v59, 1.0, v59
	v_add_f32_e32 v60, 1.0, v60
	v_add_f32_e32 v61, 1.0, v61
	v_rcp_f32_e32 v58, v58
	v_rcp_f32_e32 v59, v59
	v_rcp_f32_e32 v60, v60
	v_rcp_f32_e32 v61, v61
	v_pk_mul_f32 v[56:57], v[72:73], v[56:57]
	v_pk_mul_f32 v[112:113], v[74:75], v[112:113]
	v_pk_mul_f32 v[56:57], v[56:57], v[58:59]
	v_pk_mul_f32 v[112:113], v[112:113], v[60:61]
	v_cvt_pk_bf16_f32 v56, v56, v57
	v_cvt_pk_bf16_f32 v57, v112, v113
	global_store_dwordx2 v[48:49], v[56:57], off offset:32
	s_waitcnt vmcnt(7)
	v_lshlrev_b32_e32 v56, 16, v108
	v_and_b32_e32 v57, 0xffff0000, v108
	v_lshlrev_b32_e32 v112, 16, v109
	v_and_b32_e32 v113, 0xffff0000, v109
	v_mul_f32_e32 v58, 0xbfb8aa3b, v56
	v_mul_f32_e32 v59, 0xbfb8aa3b, v57
	v_mul_f32_e32 v60, 0xbfb8aa3b, v112
	v_mul_f32_e32 v61, 0xbfb8aa3b, v113
	v_exp_f32_e32 v58, v58
	v_exp_f32_e32 v59, v59
	v_exp_f32_e32 v60, v60
	v_exp_f32_e32 v61, v61
	v_add_f32_e32 v58, 1.0, v58
	v_add_f32_e32 v59, 1.0, v59
	v_add_f32_e32 v60, 1.0, v60
	v_add_f32_e32 v61, 1.0, v61
	v_rcp_f32_e32 v58, v58
	v_rcp_f32_e32 v59, v59
	v_rcp_f32_e32 v60, v60
	v_rcp_f32_e32 v61, v61
	v_pk_mul_f32 v[56:57], v[68:69], v[56:57]
	v_pk_mul_f32 v[112:113], v[70:71], v[112:113]
	v_pk_mul_f32 v[56:57], v[56:57], v[58:59]
	v_pk_mul_f32 v[112:113], v[112:113], v[60:61]
	v_cvt_pk_bf16_f32 v56, v56, v57
	v_cvt_pk_bf16_f32 v57, v112, v113
	global_store_dwordx2 v[48:49], v[56:57], off offset:64
	s_waitcnt vmcnt(7)
	v_lshlrev_b32_e32 v56, 16, v110
	v_and_b32_e32 v57, 0xffff0000, v110
	v_lshlrev_b32_e32 v112, 16, v111
	v_and_b32_e32 v113, 0xffff0000, v111
	v_mul_f32_e32 v58, 0xbfb8aa3b, v56
	v_mul_f32_e32 v59, 0xbfb8aa3b, v57
	v_mul_f32_e32 v60, 0xbfb8aa3b, v112
	v_mul_f32_e32 v61, 0xbfb8aa3b, v113
	v_exp_f32_e32 v58, v58
	v_exp_f32_e32 v59, v59
	v_exp_f32_e32 v60, v60
	v_exp_f32_e32 v61, v61
	v_add_f32_e32 v58, 1.0, v58
	v_add_f32_e32 v59, 1.0, v59
	v_add_f32_e32 v60, 1.0, v60
	v_add_f32_e32 v61, 1.0, v61
	v_rcp_f32_e32 v58, v58
	v_rcp_f32_e32 v59, v59
	v_rcp_f32_e32 v60, v60
	v_rcp_f32_e32 v61, v61
	v_pk_mul_f32 v[56:57], v[64:65], v[56:57]
	v_pk_mul_f32 v[112:113], v[66:67], v[112:113]
	v_pk_mul_f32 v[56:57], v[56:57], v[58:59]
	v_pk_mul_f32 v[112:113], v[112:113], v[60:61]
	v_cvt_pk_bf16_f32 v56, v56, v57
	v_cvt_pk_bf16_f32 v57, v112, v113
	global_store_dwordx2 v[48:49], v[56:57], off offset:96
	s_cbranch_vccz .LBB0_237
.LBB0_209:
	s_lshl_b32 s44, s5, 8
	s_ashr_i32 s98, s5, 4
	s_and_b32 s44, s44, 0xf00
	v_add_u32_e32 v168, s44, v207
	s_ashr_i32 s99, s98, 31
	v_or_b32_e32 v100, v168, v146
	s_lshl_b64 s[44:45], s[98:99], 19
	v_lshl_add_u64 v[48:49], v[134:135], 0, s[44:45]
	v_lshlrev_b32_e32 v132, 7, v100
	v_lshl_add_u64 v[60:61], v[48:49], 0, v[132:133]
	global_load_dwordx4 v[48:51], v[60:61], off
	global_load_dwordx4 v[52:55], v[60:61], off offset:2048
	global_load_dwordx4 v[56:59], v[60:61], off offset:64
	global_load_dwordx4 v[60:63], v[60:61], off offset:2112
	s_add_i32 s4, s5, s3
	s_cmpk_gt_i32 s4, 0x7ff
	s_cselect_b64 s[80:81], -1, 0
	s_cmpk_lt_i32 s4, 0x800
	s_cselect_b32 s1, s4, s5
	s_ashr_i32 s0, s1, 4
	s_lshl_b32 s1, s1, 8
	s_and_b32 s16, s1, 0xf00
	s_ashr_i32 s1, s0, 31
	s_add_i32 s17, s16, 0xffffff80
	s_lshl_b64 s[0:1], s[0:1], 19
	s_add_u32 s12, s20, s0
	s_addc_u32 s13, s21, s1
	s_cmp_eq_u32 s16, 0
	s_barrier
	s_waitcnt vmcnt(8)
	ds_write_b128 v215, v[0:3]
	ds_write_b128 v216, v[8:11]
	s_waitcnt vmcnt(7)
	ds_write_b128 v217, v[16:19]
	s_waitcnt vmcnt(6)
	ds_write_b128 v218, v[12:15]
	s_waitcnt vmcnt(5)
	ds_write_b128 v219, v[24:27]
	s_waitcnt vmcnt(4)
	ds_write_b128 v220, v[20:23]
	ds_write_b128 v201, v[4:7] offset:55296
	ds_write_b128 v202, v[32:35] offset:55296
	ds_write_b128 v203, v[28:31] offset:55296
	ds_write_b128 v204, v[40:43] offset:55296
	ds_write_b128 v205, v[36:39] offset:55296
	ds_write_b128 v206, v[44:47] offset:55296
	s_waitcnt lgkmcnt(0)
	s_barrier
	s_waitcnt vmcnt(0)
	s_cbranch_scc1 .LBB0_211
	v_or_b32_e32 v132, s17, v194
	v_lshlrev_b64 v[0:1], 7, v[132:133]
	v_lshl_add_u64 v[0:1], s[12:13], 0, v[0:1]
	v_lshl_add_u64 v[0:1], v[126:127], 1, v[0:1]
	global_load_dwordx4 v[0:3], v[0:1], off
	s_branch .LBB0_212

.LBB0_226:
	s_or_b64 exec, exec, s[12:13]
	s_lshl_b32 s0, s5, 8
	s_and_b32 s0, s0, 0xf00
	ds_read_b128 v[64:67], v221
	ds_read_b128 v[68:71], v221 offset:64
	ds_read_b128 v[76:79], v221 offset:2304
	ds_read_b128 v[80:83], v221 offset:2368
	v_or_b32_e32 v101, v168, v122
	v_or_b32_e32 v116, 3, v101
	v_cmp_lt_u32_e64 s[28:29], v116, v100
	v_or_b32_e32 v102, 16, v100
	v_cmp_lt_u32_e64 s[12:13], v101, v102
	v_cmp_lt_u32_e64 s[14:15], v116, v102
	s_waitcnt lgkmcnt(3)
	v_mfma_f32_16x16x32_bf16 v[72:75], v[64:67], v[48:51], 0
	s_waitcnt lgkmcnt(1)
	v_mfma_f32_16x16x32_bf16 v[84:87], v[76:79], v[48:51], 0
	v_mfma_f32_16x16x32_bf16 v[88:91], v[76:79], v[52:55], 0
	v_mfma_f32_16x16x32_bf16 v[72:75], v[68:71], v[56:59], v[72:75]
	v_mfma_f32_16x16x32_bf16 v[64:67], v[64:67], v[52:55], 0
	s_waitcnt lgkmcnt(0)
	v_mfma_f32_16x16x32_bf16 v[76:79], v[80:83], v[56:59], v[84:87]
	s_nop 4
	v_mul_f32_e64 v92, |v75|, s51
	v_mfma_f32_16x16x32_bf16 v[80:83], v[80:83], v[60:63], v[88:91]
	v_max_f32_e32 v87, v73, v73
	v_max_f32_e32 v113, 0, v87
	v_max_f32_e32 v84, v72, v72
	v_mul_f32_e64 v88, |v73|, s51
	v_mfma_f32_16x16x32_bf16 v[68:71], v[68:71], v[60:63], v[64:67]
	v_exp_f32_e32 v87, v88
	v_max_f32_e32 v104, v76, v76
	v_mul_f32_e64 v110, |v79|, s51
	v_max_f32_e32 v89, v74, v74
	v_add_f32_e32 v87, 1.0, v87
	s_nop 2
	v_max_f32_e32 v97, v70, v70
	v_mul_f32_e64 v90, |v74|, s51
	v_max_f32_e32 v91, v75, v75
	v_max_f32_e32 v93, v68, v68
	v_mul_f32_e64 v94, |v68|, s51
	v_mul_f32_e64 v96, |v69|, s51
	v_mul_f32_e64 v98, |v70|, s51
	v_mul_f32_e64 v107, |v77|, s51
	v_max_f32_e32 v111, 0, v84
	v_max_f32_e32 v84, 0, v97
	v_max_f32_e32 v97, 0, v104
	v_exp_f32_e32 v104, v110
	v_log_f32_e32 v87, v87
	v_mul_f32_e64 v105, |v76|, s51
	v_max_f32_e32 v114, 0, v89
	v_exp_f32_e32 v89, v90
	v_max_f32_e32 v115, 0, v91
	v_exp_f32_e32 v90, v92
	v_max_f32_e32 v92, 0, v93
	v_exp_f32_e32 v91, v94
	v_exp_f32_e32 v93, v96
	v_exp_f32_e32 v94, v98
	v_exp_f32_e32 v98, v107
	v_exp_f32_e32 v96, v105
	v_fmac_f32_e32 v113, 0x3f317218, v87
	v_add_f32_e32 v87, 1.0, v104
	v_max_f32_e32 v95, v69, v69
	v_mul_f32_e64 v103, |v71|, s51
	v_max_f32_e32 v106, v77, v77
	v_add_f32_e32 v93, 1.0, v93
	v_add_f32_e32 v107, 1.0, v98
	v_log_f32_e32 v87, v87
	v_or_b32_e32 v85, 16, v101
	v_max_f32_e32 v88, 0, v95
	v_exp_f32_e32 v95, v103
	v_max_f32_e32 v103, 0, v106
	v_add_f32_e32 v106, 1.0, v96
	v_log_f32_e32 v96, v93
	v_log_f32_e32 v93, v107
	v_cmp_lt_u32_e32 vcc, v85, v100
	v_max_f32_e32 v85, v79, v79
	v_mul_f32_e64 v86, |v72|, s51
	v_max_f32_e32 v99, v71, v71
	v_mul_f32_e64 v109, |v78|, s51
	v_max_f32_e32 v104, 0, v85
	v_mul_f32_e64 v85, |v80|, s51
	v_exp_f32_e32 v112, v86
	v_max_f32_e32 v86, 0, v99
	v_exp_f32_e32 v99, v109
	v_exp_f32_e32 v85, v85
	v_fmac_f32_e32 v104, 0x3f317218, v87
	v_max_f32_e32 v87, v80, v80
	v_add_f32_e32 v89, 1.0, v89
	v_fmac_f32_e32 v103, 0x3f317218, v93
	v_max_f32_e32 v93, 0, v87
	v_mul_f32_e64 v87, |v81|, s51
	v_add_f32_e32 v91, 1.0, v91
	v_log_f32_e32 v89, v89
	v_exp_f32_e32 v87, v87
	v_log_f32_e32 v98, v91
	v_log_f32_e32 v91, v106
	v_add_f32_e32 v90, 1.0, v90
	v_add_f32_e32 v94, 1.0, v94
	v_add_f32_e32 v95, 1.0, v95
	v_add_f32_e32 v99, 1.0, v99
	v_add_f32_e32 v85, 1.0, v85
	v_log_f32_e32 v109, v90
	v_log_f32_e32 v90, v94
	v_log_f32_e32 v94, v95
	v_log_f32_e32 v95, v99
	v_log_f32_e32 v99, v85
	v_max_f32_e32 v85, v81, v81
	v_fmac_f32_e32 v114, 0x3f317218, v89
	v_max_f32_e32 v89, 0, v85
	v_add_f32_e32 v85, 1.0, v87
	v_mul_f32_e64 v87, |v82|, s51
	v_fmac_f32_e32 v97, 0x3f317218, v91
	v_exp_f32_e32 v91, v87
	v_cndmask_b32_e64 v106, 0, -v97, vcc
	v_log_f32_e32 v97, v85
	v_max_f32_e32 v85, v82, v82
	v_add_f32_e32 v105, 1.0, v112
	v_max_f32_e32 v87, 0, v85
	v_add_f32_e32 v85, 1.0, v91
	v_mul_f32_e64 v91, |v83|, s51
	v_log_f32_e32 v105, v105
	v_exp_f32_e32 v91, v91
	v_max_f32_e32 v108, v78, v78
	v_fmac_f32_e32 v115, 0x3f317218, v109
	v_or_b32_e32 v109, 1, v101
	v_or_b32_e32 v112, 2, v101
	v_fmac_f32_e32 v111, 0x3f317218, v105
	v_max_f32_e32 v107, 0, v108
	v_add_f32_e32 v91, 1.0, v91
	v_cmp_lt_u32_e64 s[36:37], v109, v100
	v_cmp_lt_u32_e64 s[26:27], v112, v100
	v_cndmask_b32_e64 v105, 0, -v111, s[10:11]
	v_fmac_f32_e32 v107, 0x3f317218, v95
	v_log_f32_e32 v95, v85
	v_log_f32_e32 v91, v91
	v_cndmask_b32_e64 v110, 0, -v113, s[36:37]
	v_or_b32_e32 v111, 19, v101
	v_cndmask_b32_e64 v113, 0, -v114, s[26:27]
	v_or_b32_e32 v114, 18, v101
	v_or_b32_e32 v108, 17, v101
	v_cmp_lt_u32_e64 s[30:31], v114, v100
	v_cmp_lt_u32_e64 s[34:35], v111, v100
	v_max_f32_e32 v85, v83, v83
	v_cndmask_b32_e64 v115, 0, -v115, s[28:29]
	v_cmp_lt_u32_e64 s[38:39], v108, v100
	v_cndmask_b32_e64 v107, 0, -v107, s[30:31]
	v_cndmask_b32_e64 v100, 0, -v104, s[34:35]
	v_max_f32_e32 v85, 0, v85
	v_cndmask_b32_e64 v103, 0, -v103, s[38:39]
	v_pk_fma_f32 v[92:93], v[98:99], s[62:63], v[92:93] op_sel_hi:[1,0,1]
	v_cmp_lt_u32_e64 s[18:19], v108, v102
	v_cmp_lt_u32_e64 s[20:21], v109, v102
	v_cmp_lt_u32_e64 s[16:17], v114, v102
	v_cmp_lt_u32_e64 s[22:23], v111, v102
	v_cmp_lt_u32_e64 s[24:25], v112, v102
	v_add_f32_e32 v98, v115, v113
	v_add_f32_e32 v102, v100, v107
	v_pk_fma_f32 v[86:87], v[94:95], s[62:63], v[86:87] op_sel_hi:[1,0,1]
	v_pk_fma_f32 v[84:85], v[90:91], s[62:63], v[84:85] op_sel_hi:[1,0,1]
	v_add_f32_e32 v99, v110, v98
	v_add_f32_e32 v103, v103, v102
	v_pk_fma_f32 v[88:89], v[96:97], s[62:63], v[88:89] op_sel_hi:[1,0,1]
	v_cndmask_b32_e64 v87, 0, -v87, s[16:17]
	v_cndmask_b32_e64 v86, 0, -v86, s[14:15]
	v_cndmask_b32_e64 v85, 0, -v85, s[22:23]
	v_cndmask_b32_e64 v84, 0, -v84, s[24:25]
	v_add_f32_e32 v101, v105, v99
	v_add_f32_e32 v105, v106, v103
	v_cndmask_b32_e64 v89, 0, -v89, s[18:19]
	v_cndmask_b32_e64 v88, 0, -v88, s[20:21]
	v_pk_add_f32 v[90:91], v[84:85], v[86:87]
	v_mov_b32_e32 v84, v101
	v_mov_b32_e32 v87, v101
	v_mov_b32_e32 v94, v105
	v_mov_b32_e32 v95, v105
	v_cndmask_b32_e64 v93, 0, -v93, s[10:11]
	v_cndmask_b32_e64 v92, 0, -v92, s[12:13]
	v_pk_add_f32 v[88:89], v[88:89], v[90:91]
	v_permlane16_swap_b32_e32 v84, v87
	v_permlane16_swap_b32_e32 v94, v95
	v_pk_add_f32 v[92:93], v[92:93], v[88:89]
	v_cndmask_b32_e64 v84, v84, v87, s[8:9]
	v_cndmask_b32_e64 v94, v94, v95, s[8:9]
	v_add_f32_e32 v108, v101, v84
	v_mov_b32_e32 v84, v92
	v_mov_b32_e32 v87, v92
	v_add_f32_e32 v106, v105, v94
	v_mov_b32_e32 v94, v93
	v_mov_b32_e32 v95, v93
	v_permlane16_swap_b32_e32 v84, v87
	s_nop 0
	v_permlane16_swap_b32_e32 v94, v95
	v_cndmask_b32_e64 v95, v94, v95, s[8:9]
	v_cndmask_b32_e64 v94, v84, v87, s[8:9]
	v_mov_b32_e32 v84, v108
	v_mov_b32_e32 v87, v108
	v_mov_b32_e32 v96, v106
	v_mov_b32_e32 v97, v106
	v_pk_add_f32 v[94:95], v[92:93], v[94:95]
	v_permlane32_swap_b32_e32 v84, v87
	v_permlane32_swap_b32_e32 v96, v97
	v_cndmask_b32_e64 v109, v84, v87, s[6:7]
	v_mov_b32_e32 v84, v94
	v_mov_b32_e32 v87, v94
	v_cndmask_b32_e64 v107, v96, v97, s[6:7]
	v_mov_b32_e32 v96, v95
	v_mov_b32_e32 v97, v95
	v_permlane32_swap_b32_e32 v84, v87
	s_nop 0
	v_permlane32_swap_b32_e32 v96, v97
	v_add_f32_e32 v104, v106, v107
	v_cndmask_b32_e64 v97, v96, v97, s[6:7]
	v_cndmask_b32_e64 v96, v84, v87, s[6:7]
	v_sub_f32_e32 v84, v106, v105
	v_add_f32_e32 v87, 0, v104
	v_sub_f32_e32 v106, v108, v101
	v_fmac_f32_e32 v87, v208, v106
	v_fmac_f32_e32 v87, v209, v109
	v_add_f32_e32 v72, v72, v87
	v_add_f32_e32 v73, v73, v87
	v_add_f32_e32 v72, v101, v72
	v_add_f32_e32 v73, v99, v73
	v_mul_f32_e32 v72, 0x3fb8aa3b, v72
	v_mul_f32_e32 v73, 0x3fb8aa3b, v73
	v_exp_f32_e32 v72, v72
	v_exp_f32_e32 v73, v73
	v_fma_f32 v84, v208, v84, 0
	v_fmac_f32_e32 v84, v209, v107
	v_cndmask_b32_e64 v99, 0, v72, s[10:11]
	v_cndmask_b32_e64 v101, 0, v73, s[36:37]
	v_add_f32_e32 v72, v78, v84
	v_add_f32_e32 v73, v74, v87
	v_add_f32_e32 v72, v102, v72
	v_add_f32_e32 v73, v98, v73
	v_mul_f32_e32 v72, 0x3fb8aa3b, v72
	v_mul_f32_e32 v73, 0x3fb8aa3b, v73
	v_exp_f32_e32 v72, v72
	v_exp_f32_e32 v73, v73
	v_add_f32_e32 v74, v79, v84
	v_pk_add_f32 v[106:107], v[94:95], v[96:97]
	v_cndmask_b32_e64 v78, 0, v72, s[30:31]
	v_cndmask_b32_e64 v79, 0, v73, s[26:27]
	v_pk_add_f32 v[72:73], v[94:95], v[92:93] neg_lo:[0,1] neg_hi:[0,1]
	v_add_f32_e32 v76, v76, v84
	v_fma_f32 v73, v208, v73, 0
	v_add_f32_e32 v77, v77, v84
	v_fmac_f32_e32 v73, v209, v97
	v_add_f32_e32 v84, 0, v107
	v_fmac_f32_e32 v84, v208, v72
	v_add_f32_e32 v72, v80, v73
	v_add_f32_e32 v80, v81, v73
	v_add_f32_e32 v80, v89, v80
	v_mul_f32_e32 v80, 0x3fb8aa3b, v80
	v_exp_f32_e32 v80, v80
	v_fmac_f32_e32 v84, v209, v96
	ds_read2_b64 v[64:67], v222 offset0:32 offset1:36
	v_add_f32_e32 v75, v75, v87
	v_add_f32_e32 v68, v68, v84
	v_add_f32_e32 v69, v69, v84
	v_cndmask_b32_e64 v87, 0, v80, s[18:19]
	v_add_f32_e32 v80, v82, v73
	v_add_f32_e32 v70, v70, v84
	v_add_f32_e32 v73, v83, v73
	v_add_f32_e32 v71, v71, v84
	v_add_f32_e32 v76, v105, v76
	v_add_f32_e32 v77, v103, v77
	v_add_f32_e32 v74, v100, v74
	v_add_f32_e32 v75, v115, v75
	v_add_f32_e32 v72, v93, v72
	v_add_f32_e32 v68, v92, v68
	v_add_f32_e32 v69, v88, v69
	v_add_f32_e32 v80, v91, v80
	v_add_f32_e32 v70, v90, v70
	v_add_f32_e32 v73, v85, v73
	v_add_f32_e32 v71, v86, v71
	v_mul_f32_e32 v76, 0x3fb8aa3b, v76
	v_mul_f32_e32 v77, 0x3fb8aa3b, v77
	v_mul_f32_e32 v74, 0x3fb8aa3b, v74
	v_mul_f32_e32 v75, 0x3fb8aa3b, v75
	v_mul_f32_e32 v72, 0x3fb8aa3b, v72
	v_mul_f32_e32 v68, 0x3fb8aa3b, v68
	v_mul_f32_e32 v69, 0x3fb8aa3b, v69
	v_mul_f32_e32 v80, 0x3fb8aa3b, v80
	v_mul_f32_e32 v70, 0x3fb8aa3b, v70
	v_mul_f32_e32 v73, 0x3fb8aa3b, v73
	v_mul_f32_e32 v71, 0x3fb8aa3b, v71
	v_exp_f32_e32 v76, v76
	v_exp_f32_e32 v77, v77
	v_exp_f32_e32 v74, v74
	v_exp_f32_e32 v75, v75
	v_exp_f32_e32 v72, v72
	v_exp_f32_e32 v68, v68
	v_exp_f32_e32 v69, v69
	v_exp_f32_e32 v80, v80
	v_exp_f32_e32 v70, v70
	v_exp_f32_e32 v73, v73
	v_exp_f32_e32 v71, v71
	v_cndmask_b32_e32 v76, 0, v76, vcc
	v_cndmask_b32_e64 v77, 0, v77, s[38:39]
	v_cndmask_b32_e64 v74, 0, v74, s[34:35]
	v_cndmask_b32_e64 v75, 0, v75, s[28:29]
	v_cndmask_b32_e64 v72, 0, v72, s[10:11]
	v_cndmask_b32_e64 v68, 0, v68, s[12:13]
	v_cndmask_b32_e64 v69, 0, v69, s[20:21]
	v_cndmask_b32_e64 v84, 0, v80, s[16:17]
	v_cndmask_b32_e64 v70, 0, v70, s[24:25]
	v_cndmask_b32_e64 v73, 0, v73, s[22:23]
	v_cndmask_b32_e64 v71, 0, v71, s[14:15]
	v_cvt_pk_bf16_f32 v80, v99, v101
	v_cvt_pk_bf16_f32 v81, v79, v75
	v_cvt_pk_bf16_f32 v82, v76, v77
	v_cvt_pk_bf16_f32 v83, v78, v74
	v_cvt_pk_bf16_f32 v96, v68, v69
	v_cvt_pk_bf16_f32 v97, v70, v71
	v_cvt_pk_bf16_f32 v98, v72, v87
	v_cvt_pk_bf16_f32 v99, v84, v73
	s_waitcnt lgkmcnt(0)
	v_mfma_f32_16x16x32_bf16 v[92:95], v[64:67], v[80:83], 0
	ds_read2_b64 v[100:103], v212 offset1:4
	s_add_i32 s14, s0, 0xffffff80
	s_cmp_eq_u32 s0, 0
	v_mfma_f32_16x16x32_bf16 v[76:79], v[64:67], v[96:99], 0
	ds_read2_b64 v[64:67], v210 offset1:4
	s_cselect_b64 s[12:13], -1, 0
	v_mov_b32_e32 v105, v107
	s_waitcnt lgkmcnt(0)
	v_mfma_f32_16x16x32_bf16 v[88:91], v[64:67], v[80:83], 0
	s_and_b64 s[0:1], s[12:13], exec
	s_cselect_b32 s22, 0, s14
	v_mfma_f32_16x16x32_bf16 v[72:75], v[64:67], v[96:99], 0
	ds_read2_b64 v[64:67], v211 offset1:4
	s_waitcnt lgkmcnt(0)
	v_mfma_f32_16x16x32_bf16 v[84:87], v[64:67], v[80:83], 0
	v_mfma_f32_16x16x32_bf16 v[68:71], v[64:67], v[96:99], 0
	v_add_f32_e32 v64, v108, v109
	v_mov_b32_e32 v65, v106
	v_pk_add_f32 v[104:105], v[64:65], v[104:105]
	v_mfma_f32_16x16x32_bf16 v[80:83], v[100:103], v[80:83], 0
	v_cmp_gt_f32_e32 vcc, s63, v104
	v_cmp_gt_f32_e64 s[0:1], s63, v105
	s_and_b64 s[0:1], vcc, s[0:1]
	v_mfma_f32_16x16x32_bf16 v[64:67], v[100:103], v[96:99], 0
	v_cndmask_b32_e64 v96, 0, 1, s[0:1]
	v_cmp_ne_u32_e32 vcc, 0, v96
	v_pk_add_f32 v[170:171], v[104:105], 0 op_sel_hi:[1,0]
	s_cmp_eq_u64 vcc, exec
	s_mov_b64 s[0:1], -1
	s_cbranch_scc1 .LBB0_232
	v_cmp_lt_i32_e32 vcc, s22, v168
	s_mov_b64 s[0:1], 0
	s_and_saveexec_b64 s[14:15], vcc
	s_cbranch_execz .LBB0_231
	s_and_b32 s0, s33, 0xf00
	v_add_u32_e32 v112, s0, v213
	s_mov_b64 s[16:17], 0
	v_mov_b32_e32 v113, v214
	v_mov_b32_e32 v114, v125
